# MX: next chunk's Q loads issued before the end-of-step barrier (after the Q staging writes) instead of at the top of the next step
# speedup vs baseline: 1.0198x; 1.0091x over previous
; #define MX_BAR() do { asm volatile("s_waitcnt lgkmcnt(0)" ::: "memory"); __builtin_amdgcn_s_barrier(); asm volatile("" ::: "memory"); } while (0)
; #define MX_LOADK(ch) do { const int r0_ = lrowb + (ch) * 64; const char* kr_ = (const char*)(kb + (size_t)r0_ * qpitch); \
;             _Pragma("unroll") for (int i = 0; i < 4; ++i) pk[i] = *(const u32x4*)(kr_ + i * qstep16 + voq); \
;             if (tid < 256) pv = *(const u32x4*)((const char*)(vb + (size_t)r0_ * NPC) + vov); } while (0)
; #define MX_STAGEQ() do { int ts_ = tid; \
;             _Pragma("unroll") for (int i = 0; i < 4; ++i) { const int idx = ts_ + 512 * i, row = idx >> 5, c16 = idx & 31; \
;                 *(LAS u32x4*)(lds + L_QI + row * QP + c16 * 16) = pq[i]; } } while (0)
; DI void phase_mixer(const Params& p, int seg, LAS unsigned char* lds, int G, int bid) {
;     ...
;         u32x4 pq[4], pk[4], pv; u32x2 pin[2]; float pden = 0.f, pcm = 0.f, pbc = 0.f, pmch = 0.f;
;         const unsigned voq = (unsigned)(((tid >> 5) * qpitch + (tid & 31) * 8) * 2);
;         const unsigned vov = (unsigned)(((tid >> 2) * NPC + (tid & 3) * 8) * 2);
;         const unsigned vop = (unsigned)(((16 * ((tid >> 6) & 3) + (tid & 15)) * NPC + 4 * ((tid & 63) >> 4)) * 2);
;         const size_t qstep16 = (size_t)16 * qpitch * 2;
;     ...
;         u32x2 cin[2]; float cden = 0.f, cemr = 1.f;
;         MX_LOADQ(0);
;         MX_LOADK(0);
;         MX_STAGEQ();
;         cin[0] = pin[0]; cin[1] = pin[1]; cden = pden; cemr = __expf(-(pbc + fmaxf(pmch, pcm)));
;         MX_BAR();
;         for (int ch = 0; ch < NCH; ++ch) {
;             float g_n = 1.f;
;             if (ch + 1 < NCH) { g_n = MX_G(ch + 1); MX_LOADQ(ch + 1); }
.LBB0_592:
	s_or_b64 exec, exec, s[50:51]
	s_and_b32 s31, s22, 3
	s_lshr_b32 s6, s8, 2
	s_lshl_b32 s50, s31, 12
	s_and_b32 s22, s39, 3
	s_and_b32 s18, s38, 0xfffffc00
	v_or_b32_e32 v2, s50, v161
	s_lshl_b32 s51, s22, 2
	s_and_b32 s6, s6, 7
	s_ashr_i32 s19, s18, 31
	v_lshl_or_b32 v3, v2, 4, s51
	s_lshl_b32 s6, s6, 6
	s_lshl_b64 s[18:19], s[18:19], 1
	v_or_b32_e32 v172, 0x500000, v3
	v_mul_hi_u32_u24_e32 v3, 0x4800, v2
	v_mul_u32_u24_e32 v2, 0x4800, v2
	s_lshl_b32 s33, s22, 9
	s_or_b32 s28, s18, s6
	v_or_b32_e32 v2, v146, v2
	s_or_b32 s28, s28, s33
	s_mov_b32 s29, s19
	v_lshl_add_u64 v[174:175], s[28:29], 0, v[2:3]
	s_lshl_b32 s84, s22, 4
	s_lshl_b64 s[28:29], s[26:27], 4
	s_add_u32 s35, s84, s28
	s_addc_u32 s22, 0, s29
	s_or_b32 s26, s6, s33
	s_mul_i32 s28, s31, 0x4800000
	s_or_b64 s[18:19], s[26:27], s[18:19]
	s_add_u32 s18, s18, s28
	s_addc_u32 s19, s19, 0
	s_lshl_b32 s6, s31, 13
	v_or_b32_e32 v2, s50, v227
	s_or_b32 s29, s6, 0xc0
	s_or_b32 s31, s6, 0xe0
	s_or_b32 s50, s6, 0xa0
	s_cmp_eq_u32 vcc_hi, 0
	v_lshl_add_u64 v[180:181], s[18:19], 0, v[150:151]
	s_cselect_b64 s[18:19], -1, 0
	s_and_b64 s[18:19], s[78:79], s[18:19]
	v_lshl_or_b32 v176, v2, 6, s84
	s_and_b64 s[84:85], s[18:19], s[44:45]
	s_or_b32 s18, s26, s28
	s_add_u32 s18, s18, s53
	s_addc_u32 s19, 0, 0
	s_bitset1_b32 s6, 7
	s_mul_i32 s6, s6, vcc_lo
	v_lshl_add_u64 v[182:183], s[18:19], 0, v[148:149]
	s_add_u32 s18, s23, s6
	s_addc_u32 s19, 0, 0
	s_add_u32 s18, s18, s33
	s_addc_u32 s19, s19, 0
	s_lshl_b32 s26, vcc_lo, 7
	s_mul_i32 s29, s29, vcc_lo
	v_lshl_add_u64 v[184:185], s[18:19], 0, v[0:1]
	s_add_u32 s18, s23, s29
	s_addc_u32 s19, 0, 0
	s_add_u32 s18, s18, s33
	s_addc_u32 s19, s19, 0
	s_mul_i32 s31, s31, vcc_lo
	v_lshl_add_u64 v[186:187], s[18:19], 0, v[0:1]
	s_add_u32 s18, s23, s31
	s_addc_u32 s19, 0, 0
	s_add_u32 s18, s18, s33
	s_addc_u32 s19, s19, 0
	s_mul_i32 s50, s50, vcc_lo
	v_lshl_add_u64 v[188:189], s[18:19], 0, v[0:1]
	s_add_u32 s18, s23, s50
	s_addc_u32 s19, 0, 0
	s_add_u32 s18, s18, s33
	s_addc_u32 s19, s19, 0
	s_add_u32 s6, s52, s6
	v_lshl_add_u64 v[190:191], s[18:19], 0, v[0:1]
	s_addc_u32 s19, 0, 0
	s_add_u32 s18, s6, s33
	s_addc_u32 s19, s19, 0
	s_add_u32 s6, s52, s29
	v_lshl_add_u64 v[192:193], s[18:19], 0, v[0:1]
	s_addc_u32 s19, 0, 0
	s_add_u32 s18, s6, s33
	s_addc_u32 s19, s19, 0
	v_lshl_or_b32 v2, v2, 4, s51
	s_add_u32 s6, s52, s31
	v_or_b32_e32 v178, 0x580000, v2
	s_waitcnt vmcnt(6)
	v_max_f32_e32 v2, v234, v234
	s_waitcnt vmcnt(4)
	v_max_f32_e32 v3, v235, v235
	v_lshl_add_u64 v[194:195], s[18:19], 0, v[0:1]
	s_addc_u32 s19, 0, 0
	v_max_f32_e32 v2, v3, v2
	s_add_u32 s18, s6, s33
	v_add_f32_e32 v2, v236, v2
	s_addc_u32 s19, s19, 0
	v_mul_f32_e32 v2, 0xbfb8aa3b, v2
	s_add_u32 s6, s52, s50
	ds_write_b128 v229, v[48:51]
	ds_write_b128 v230, v[52:55]
	ds_write_b128 v231, v[56:59]
	ds_write_b128 v232, v[60:63]
	v_exp_f32_e32 v237, v2
	v_lshl_add_u64 v[196:197], s[18:19], 0, v[0:1]
	s_addc_u32 s19, 0, 0
	s_waitcnt lgkmcnt(0)
	s_barrier
	s_add_u32 s18, s6, s33
	s_addc_u32 s19, s19, 0
	v_mov_b32_e32 v173, v1
	v_mov_b32_e32 v177, v1
	v_mov_b32_e32 v179, v1
	v_lshl_add_u64 v[198:199], s[18:19], 0, v[0:1]
	s_bfe_u32 s32, s8, 0x30002
	s_lshl_b32 s98, s32, 6
	v_add_u32_e32 v244, s98, v224
	v_add_u32_e32 v245, s98, v163
	v_lshrrev_b32_e32 v246, 6, v202
	s_lshl_b32 s98, s32, 2
	s_add_u32 s98, s92, s98
	s_addc_u32 s99, s93, 0
	s_sub_u32 s98, s98, 0x2000000
	s_subb_u32 s99, s99, 0
	s_add_u32 s100, s92, 0x580000
	s_addc_u32 s101, s93, 0
	v_readfirstlane_b32 vcc_lo, v246
	s_nop 3
	s_cmp_eq_u32 vcc_lo, s32
	s_cselect_b32 s32, 1, 0
	v_lshl_add_u64 v[246:247], s[92:93], 0, v[184:185]
	v_lshl_add_u64 v[248:249], s[92:93], 0, v[190:191]
	global_load_dwordx4 v[48:51], v[246:247], off
	global_load_dwordx4 v[52:55], v[248:249], off
	v_lshl_add_u64 v[246:247], s[92:93], 0, v[186:187]
	v_lshl_add_u64 v[248:249], s[92:93], 0, v[188:189]
	global_load_dwordx4 v[56:59], v[246:247], off
	global_load_dwordx4 v[60:63], v[248:249], off
	s_mov_b32 s23, 64
	v_mov_b64_e32 v[2:3], v[156:157]
	v_mov_b64_e32 v[200:201], v[154:155]
	s_andn2_b64 vcc, exec, s[78:79]
	v_mov_b32_e32 v160, v153
	s_cbranch_vccnz .LBB0_594

; DI void phase_mixer(const Params& p, int seg, LAS unsigned char* lds, int G, int bid) {
;     ...
;             if (ch + 1 < NCH) { g_n = MX_G(ch + 1); MX_LOADQ(ch + 1); }
.LBB0_594:
	v_mov_b32_e32 v238, v239
	v_mov_b64_e32 v[154:155], v[200:201]
	v_mov_b64_e32 v[156:157], v[2:3]
	s_and_saveexec_b64 s[50:51], s[42:43]
	s_cbranch_execz .LBB0_598
	v_lshl_add_u64 v[64:65], s[92:93], 0, v[180:181]
	v_add_co_u32_e32 v64, vcc, 0xc120000, v64
	v_mov_b32_e32 v238, v239
	s_nop 0
	v_addc_co_u32_e32 v65, vcc, 0, v65, vcc
	global_load_dwordx2 v[154:155], v[64:65], off
	global_load_dwordx2 v[156:157], v[64:65], off offset:32
	s_and_saveexec_b64 s[52:53], s[84:85]
	s_cbranch_execz .LBB0_597
	v_lshl_add_u64 v[64:65], s[92:93], 0, v[176:177]
	v_add_co_u32_e32 v64, vcc, 0x300000, v64
	s_add_u32 s18, s92, s35
	v_lshl_add_u64 v[66:67], s[92:93], 0, v[178:179]
	v_addc_co_u32_e32 v65, vcc, 0, v65, vcc
	s_addc_u32 s19, s93, s22
	global_load_dword v238, v[66:67], off
	global_load_dword v234, v[64:65], off
	global_load_dword v236, v[64:65], off offset:8
	global_load_dword v235, v208, s[18:19] offset:76

; #define MX_BAR() do { asm volatile("s_waitcnt lgkmcnt(0)" ::: "memory"); __builtin_amdgcn_s_barrier(); asm volatile("" ::: "memory"); } while (0)
; #define MX_STAGEQ() do { int ts_ = tid; \
;             _Pragma("unroll") for (int i = 0; i < 4; ++i) { const int idx = ts_ + 512 * i, row = idx >> 5, c16 = idx & 31; \
;                 *(LAS u32x4*)(lds + L_QI + row * QP + c16 * 16) = pq[i]; } } while (0)
; DI void phase_mixer(const Params& p, int seg, LAS unsigned char* lds, int G, int bid) {
;     ...
;             MX_WRITE_CIMG(1.0f);
;             if (ch + 1 < NCH) { MX_STAGEQ(); cin[0] = pin[0]; cin[1] = pin[1]; cden = pden; cemr = __expf(-(pbc + fmaxf(pmch, pcm))); }
;             MX_BAR();
;             g_c = g_n;
.Lmx_wq2:
	s_nop 1
	v_lshl_add_u64 v[246:247], s[92:93], 0, v[184:185]
	v_lshl_add_u64 v[248:249], s[92:93], 0, v[190:191]
	global_load_dwordx4 v[48:51], v[246:247], off
	global_load_dwordx4 v[52:55], v[248:249], off
	v_lshl_add_u64 v[246:247], s[92:93], 0, v[186:187]
	v_lshl_add_u64 v[248:249], s[92:93], 0, v[188:189]
	global_load_dwordx4 v[56:59], v[246:247], off
	global_load_dwordx4 v[60:63], v[248:249], off
	v_max_f32_e32 v2, v235, v235
	v_max_f32_e32 v0, v2, v0
	v_add_f32_e32 v0, v236, v0
	v_mul_f32_e32 v0, 0xbfb8aa3b, v0
	v_exp_f32_e32 v237, v0
	s_waitcnt lgkmcnt(0)
	s_barrier
	s_cmp_eq_u32 s23, 0
	s_cbranch_scc1 .LBB0_612
	v_mov_b32_e32 v158, v160
	v_mov_b64_e32 v[2:3], v[156:157]
	v_mov_b64_e32 v[200:201], v[154:155]
	v_mov_b32_e32 v239, v238
	s_andn2_b64 vcc, exec, s[78:79]
	v_mov_b32_e32 v160, v153
	s_cbranch_vccz .LBB0_593
	s_branch .LBB0_594
